# nt (non-temporal) cache policy on the read-once f32 weight loads of the conversion phases 0/1
# speedup vs baseline: 1.0172x; 1.0156x over previous
.LBB0_17:
	v_writelane_b32 v254, s16, 10
	s_load_dwordx16 s[16:31], s[0:1], 0x0
	s_add_u32 s84, s94, 0x1200000
	s_addc_u32 s85, s95, 0
	s_add_u32 s86, s94, 0x4600000
	s_addc_u32 s87, s95, 0
	s_waitcnt lgkmcnt(0)
	v_writelane_b32 v254, s16, 11
	s_load_dwordx16 s[56:71], s[0:1], 0x80
	s_cmp_lt_i32 s12, 1
	v_writelane_b32 v254, s17, 12
	v_writelane_b32 v254, s18, 13
	v_writelane_b32 v254, s19, 14
	v_writelane_b32 v254, s20, 15
	v_writelane_b32 v254, s21, 16
	v_writelane_b32 v254, s22, 17
	v_writelane_b32 v254, s23, 18
	v_writelane_b32 v254, s24, 19
	v_writelane_b32 v254, s25, 20
	v_writelane_b32 v254, s26, 21
	v_writelane_b32 v254, s27, 22
	v_writelane_b32 v254, s28, 23
	s_cselect_b64 s[4:5], -1, 0
	s_cmp_gt_i32 s13, 0
	v_writelane_b32 v254, s29, 24
	s_cselect_b64 s[6:7], -1, 0
	v_writelane_b32 v254, s30, 25
	s_and_b64 s[8:9], s[4:5], s[6:7]
	v_writelane_b32 v254, s31, 26
	s_andn2_b64 vcc, exec, s[8:9]
	v_lshrrev_b32_e32 v145, 6, v175
	s_cbranch_vccnz .LBB0_33
	s_lshl_b32 s4, s2, 3
	v_add_u32_e32 v0, s4, v145
	s_movk_i32 s3, 0x1200
	v_cmp_gt_i32_e32 vcc, s3, v0
	s_and_saveexec_b64 s[10:11], vcc
	s_cbranch_execz .LBB0_25
	s_mov_b32 s16, 0x38e38e39
	v_mul_hi_i32 v1, v0, s16
	v_lshrrev_b32_e32 v2, 31, v1
	v_ashrrev_i32_e32 v1, 6, v1
	v_add_u32_e32 v1, v1, v2
	v_mul_i32_i24_e32 v2, 0x120, v1
	v_sub_u32_e32 v0, v0, v2
	v_bfe_u32 v7, v175, 3, 3
	v_lshlrev_b32_e32 v0, 5, v0
	v_lshlrev_b32_e32 v2, 6, v1
	s_mov_b32 s17, 0x9000
	s_waitcnt lgkmcnt(0)
	v_mov_b64_e32 v[4:5], s[68:69]
	v_or_b32_e32 v13, 8, v7
	v_mad_i64_i32 v[4:5], s[6:7], v2, s17, v[4:5]
	v_ashrrev_i32_e32 v1, 31, v0
	v_lshlrev_b32_e32 v3, 2, v175
	v_mov_b32_e32 v65, 0
	v_mul_u32_u24_e32 v12, 0x2400, v7
	v_mul_u32_u24_e32 v14, 0x2400, v13
	v_lshl_add_u64 v[4:5], v[0:1], 2, v[4:5]
	v_and_b32_e32 v6, 28, v3
	v_lshlrev_b32_e32 v64, 2, v12
	v_lshlrev_b32_e32 v10, 2, v14
	v_mov_b32_e32 v11, v65
	v_lshl_add_u64 v[8:9], v[4:5], 0, v[64:65]
	v_lshlrev_b32_e32 v64, 2, v6
	v_lshl_add_u64 v[10:11], v[4:5], 0, v[10:11]
	v_or_b32_e32 v15, 16, v7
	v_or_b32_e32 v17, 24, v7
	v_lshl_add_u64 v[8:9], v[8:9], 0, v[64:65]
	v_lshl_add_u64 v[10:11], v[10:11], 0, v[64:65]
	v_mul_u32_u24_e32 v16, 0x2400, v15
	v_mul_u32_u24_e32 v18, 0x2400, v17
	global_load_dwordx4 v[60:63], v[8:9], off nt
	global_load_dwordx4 v[52:55], v[10:11], off nt
	v_lshlrev_b32_e32 v10, 2, v16
	v_mov_b32_e32 v11, v65
	v_lshlrev_b32_e32 v20, 2, v18
	v_mov_b32_e32 v21, v65
	v_lshl_add_u64 v[10:11], v[4:5], 0, v[10:11]
	v_lshl_add_u64 v[4:5], v[4:5], 0, v[20:21]
	v_lshl_add_u64 v[10:11], v[10:11], 0, v[64:65]
	v_lshl_add_u64 v[4:5], v[4:5], 0, v[64:65]
	s_mov_b32 s18, 0x120000
	global_load_dwordx4 v[56:59], v[10:11], off nt
	global_load_dwordx4 v[40:43], v[4:5], off nt
	v_add_co_u32_e32 v4, vcc, s18, v8
	s_mov_b32 s5, 0x168000
	s_nop 0
	v_addc_co_u32_e32 v5, vcc, 0, v9, vcc
	v_add_co_u32_e32 v10, vcc, s5, v8
	s_mov_b32 s5, 0x1b0000
	s_nop 0
	v_addc_co_u32_e32 v11, vcc, 0, v9, vcc
	global_load_dwordx4 v[36:39], v[4:5], off nt
	global_load_dwordx4 v[24:27], v[10:11], off nt
	v_add_co_u32_e32 v4, vcc, s5, v8
	s_mov_b32 s5, 0x1f8000
	s_nop 0
	v_addc_co_u32_e32 v5, vcc, 0, v9, vcc
	v_add_co_u32_e32 v8, vcc, s5, v8
	v_lshlrev_b64 v[0:1], 11, v[0:1]
	s_nop 0
	v_addc_co_u32_e32 v9, vcc, 0, v9, vcc
	global_load_dwordx4 v[20:23], v[4:5], off nt
	s_nop 0
	global_load_dwordx4 v[8:11], v[8:9], off nt
	v_ashrrev_i32_e32 v3, 31, v2
	v_lshl_add_u64 v[0:1], s[84:85], 0, v[0:1]
	s_lshl_b32 s19, s34, 3
	v_lshl_add_u64 v[86:87], v[2:3], 1, v[0:1]
	v_lshlrev_b32_e32 v0, 3, v175
	v_lshl_add_u32 v4, v145, 14, 0
	v_and_b32_e32 v0, 56, v0
	s_add_i32 s4, s4, s19
	v_add_u32_e32 v1, v4, v64
	v_mul_u32_u24_e32 v2, 0x84, v7
	v_mul_u32_u24_e32 v3, 0x84, v0
	v_lshlrev_b32_e32 v5, 2, v7
	v_add_u32_e32 v89, s4, v145
	v_add3_u32 v88, v4, v3, v5
	v_lshlrev_b32_e32 v66, 11, v7
	v_mov_b32_e32 v67, v65
	v_lshlrev_b32_e32 v68, 11, v13
	v_mov_b32_e32 v69, v65
	v_lshlrev_b32_e32 v70, 11, v15
	v_mov_b32_e32 v71, v65
	v_lshlrev_b32_e32 v64, 1, v0
	v_lshlrev_b32_e32 v72, 11, v17
	v_mov_b32_e32 v73, v65
	v_add_u32_e32 v90, v1, v2
	v_lshlrev_b32_e32 v91, 5, v89
	s_lshl_b32 s20, s34, 8
	s_mov_b64 s[12:13], 0
	v_lshlrev_b32_e32 v74, 2, v12
	v_lshlrev_b32_e32 v76, 2, v6
	v_lshlrev_b32_e32 v78, 2, v14
	v_lshlrev_b32_e32 v80, 2, v16
	v_lshlrev_b32_e32 v82, 2, v18
	v_mov_b64_e32 v[84:85], v[86:87]
	s_branch .LBB0_21

.LBB0_21:
	v_cmp_gt_i32_e64 s[4:5], s3, v89
	s_and_saveexec_b64 s[6:7], s[4:5]
	s_cbranch_execz .LBB0_23
	v_mul_hi_i32 v0, v89, s16
	v_lshrrev_b32_e32 v1, 31, v0
	v_ashrrev_i32_e32 v0, 6, v0
	v_add_u32_e32 v0, v0, v1
	v_mul_i32_i24_e32 v1, 0x120, v0
	v_lshlrev_b32_e32 v1, 5, v1
	v_sub_u32_e32 v84, v91, v1
	v_lshlrev_b32_e32 v92, 6, v0
	v_mov_b64_e32 v[0:1], s[68:69]
	v_mad_i64_i32 v[0:1], s[14:15], v92, s17, v[0:1]
	v_ashrrev_i32_e32 v85, 31, v84
	v_lshl_add_u64 v[12:13], v[84:85], 2, v[0:1]
	v_mov_b32_e32 v75, v65
	v_lshl_add_u64 v[0:1], v[12:13], 0, v[74:75]
	v_mov_b32_e32 v77, v65
	v_lshl_add_u64 v[44:45], v[0:1], 0, v[76:77]
	v_add_co_u32_e32 v28, vcc, s18, v44
	v_mov_b32_e32 v79, v65
	s_nop 0
	v_addc_co_u32_e32 v29, vcc, 0, v45, vcc
	v_add_co_u32_e32 v32, vcc, 0x168000, v44
	v_mov_b32_e32 v81, v65
	s_nop 0
	v_addc_co_u32_e32 v33, vcc, 0, v45, vcc
	v_add_co_u32_e32 v46, vcc, 0x1b0000, v44
	v_mov_b32_e32 v83, v65
	s_nop 0
	v_addc_co_u32_e32 v47, vcc, 0, v45, vcc
	v_lshl_add_u64 v[0:1], v[12:13], 0, v[78:79]
	v_lshl_add_u64 v[14:15], v[12:13], 0, v[80:81]
	v_lshl_add_u64 v[12:13], v[12:13], 0, v[82:83]
	v_add_co_u32_e32 v48, vcc, 0x1f8000, v44
	v_lshl_add_u64 v[0:1], v[0:1], 0, v[76:77]
	v_lshl_add_u64 v[14:15], v[14:15], 0, v[76:77]
	v_lshl_add_u64 v[12:13], v[12:13], 0, v[76:77]
	v_addc_co_u32_e32 v49, vcc, 0, v45, vcc
	global_load_dwordx4 v[4:7], v[44:45], off nt
	s_nop 0
	global_load_dwordx4 v[0:3], v[0:1], off nt
	s_nop 0
	global_load_dwordx4 v[16:19], v[14:15], off nt
	s_nop 0
	global_load_dwordx4 v[12:15], v[12:13], off nt
	s_nop 0
	global_load_dwordx4 v[28:31], v[28:29], off nt
	s_nop 0
	global_load_dwordx4 v[32:35], v[32:33], off nt
	s_nop 0
	global_load_dwordx4 v[44:47], v[46:47], off nt
	s_nop 0
	global_load_dwordx4 v[48:51], v[48:49], off nt
	v_lshlrev_b64 v[84:85], 11, v[84:85]
	v_ashrrev_i32_e32 v93, 31, v92
	v_lshl_add_u64 v[84:85], s[84:85], 0, v[84:85]
	v_lshl_add_u64 v[84:85], v[92:93], 1, v[84:85]

.LBB0_153:
	s_or_b64 exec, exec, s[0:1]
	v_lshrrev_b32_e32 v66, 3, v4
	v_mul_u32_u24_e32 v3, v2, v66
	v_or_b32_e32 v70, 8, v66
	v_and_b32_e32 v34, 28, v142
	v_mov_b32_e32 v69, 0
	v_lshlrev_b32_e32 v68, 2, v3
	v_mul_u32_u24_e32 v3, v2, v70
	v_lshl_add_u64 v[4:5], v[0:1], 0, v[68:69]
	v_lshlrev_b32_e32 v68, 2, v34
	v_lshlrev_b32_e32 v6, 2, v3
	v_mov_b32_e32 v7, v69
	v_or_b32_e32 v72, 16, v66
	v_lshl_add_u64 v[4:5], v[4:5], 0, v[68:69]
	v_lshl_add_u64 v[6:7], v[0:1], 0, v[6:7]
	v_mul_u32_u24_e32 v3, v2, v72
	v_or_b32_e32 v74, 24, v66
	v_lshl_add_u64 v[6:7], v[6:7], 0, v[68:69]
	global_load_dwordx4 v[28:31], v[4:5], off nt
	global_load_dwordx4 v[20:23], v[6:7], off nt
	v_lshlrev_b32_e32 v4, 2, v3
	v_mov_b32_e32 v5, v69
	v_mul_u32_u24_e32 v3, v2, v74
	v_lshl_add_u64 v[4:5], v[0:1], 0, v[4:5]
	v_lshlrev_b32_e32 v6, 2, v3
	v_mov_b32_e32 v7, v69
	v_or_b32_e32 v71, 32, v66
	v_lshl_add_u64 v[4:5], v[4:5], 0, v[68:69]
	v_lshl_add_u64 v[6:7], v[0:1], 0, v[6:7]
	v_mul_u32_u24_e32 v3, v2, v71
	v_or_b32_e32 v73, 40, v66
	v_lshl_add_u64 v[6:7], v[6:7], 0, v[68:69]
	global_load_dwordx4 v[24:27], v[4:5], off nt
	global_load_dwordx4 v[12:15], v[6:7], off nt
	v_lshlrev_b32_e32 v4, 2, v3
	v_mul_u32_u24_e32 v3, v2, v73
	v_or_b32_e32 v75, 48, v66
	v_or_b32_e32 v77, 56, v66
	v_lshlrev_b32_e32 v6, 2, v3
	v_mul_u32_u24_e32 v3, v2, v75
	v_mul_u32_u24_e32 v2, v2, v77
	v_mov_b32_e32 v5, v69
	v_mov_b32_e32 v7, v69
	v_lshlrev_b32_e32 v8, 2, v3
	v_mov_b32_e32 v9, v69
	v_lshlrev_b32_e32 v2, 2, v2
	v_mov_b32_e32 v3, v69
	v_lshl_add_u64 v[4:5], v[0:1], 0, v[4:5]
	v_lshl_add_u64 v[6:7], v[0:1], 0, v[6:7]
	v_lshl_add_u64 v[8:9], v[0:1], 0, v[8:9]
	v_lshl_add_u64 v[0:1], v[0:1], 0, v[2:3]
	v_lshl_add_u64 v[4:5], v[4:5], 0, v[68:69]
	v_lshl_add_u64 v[6:7], v[6:7], 0, v[68:69]
	v_lshl_add_u64 v[8:9], v[8:9], 0, v[68:69]
	v_lshl_add_u64 v[0:1], v[0:1], 0, v[68:69]
	global_load_dwordx4 v[16:19], v[4:5], off nt
	s_nop 0
	global_load_dwordx4 v[4:7], v[6:7], off nt
	s_nop 0
	global_load_dwordx4 v[8:11], v[8:9], off nt
	s_nop 0
	global_load_dwordx4 v[0:3], v[0:1], off nt
	v_readlane_b32 s0, v255, 3
	v_lshlrev_b32_e32 v36, 3, v175
	s_lshl_b32 s3, s0, 3
	v_lshl_add_u32 v33, v145, 14, 0
	v_and_b32_e32 v36, 56, v36
	v_add_u32_e32 v35, v33, v68
	v_mul_u32_u24_e32 v37, 0x84, v66
	v_mul_u32_u24_e32 v38, 0x84, v36
	v_lshlrev_b32_e32 v39, 2, v66
	v_add_u32_e32 v86, s3, v32
	v_mov_b32_e32 v32, 0x1b900
	v_add3_u32 v79, v33, v38, v39
	v_lshlrev_b32_e32 v76, 5, v86
	s_lshl_b32 s10, s0, 8
	v_lshlrev_b32_e32 v78, 6, v86
	s_lshl_b32 s11, s0, 9
	v_lshl_add_u32 v87, v86, 1, v32
	s_lshl_b32 s12, s0, 4
	s_mov_b64 s[68:69], 0
	s_movk_i32 s13, 0x1600
	s_movk_i32 s14, 0x60
	s_mov_b32 s15, 0xffc0
	s_movk_i32 s16, 0x2c00
	s_mov_b64 s[70:71], 0x40000
	v_lshlrev_b32_e32 v80, 2, v34
	v_add_u32_e32 v88, v35, v37
	v_lshlrev_b32_e32 v82, 1, v36
	v_mov_b64_e32 v[84:85], v[64:65]
	v_mov_b32_e32 v89, v67
	s_branch .LBB0_155

.LBB0_190:
	s_or_b64 exec, exec, s[0:1]
	v_mul_u32_u24_e32 v32, v58, v66
	v_lshlrev_b32_e32 v68, 2, v32
	v_mul_u32_u24_e32 v34, v58, v70
	v_lshl_add_u64 v[32:33], v[56:57], 0, v[68:69]
	v_lshlrev_b32_e32 v68, 2, v34
	v_mul_u32_u24_e32 v40, v58, v72
	v_lshl_add_u64 v[34:35], v[56:57], 0, v[68:69]
	v_lshlrev_b32_e32 v68, 2, v40
	v_mul_u32_u24_e32 v42, v58, v74
	v_lshl_add_u64 v[40:41], v[56:57], 0, v[68:69]
	v_lshlrev_b32_e32 v68, 2, v42
	v_mul_u32_u24_e32 v48, v58, v71
	v_lshl_add_u64 v[42:43], v[56:57], 0, v[68:69]
	v_lshlrev_b32_e32 v68, 2, v48
	v_mul_u32_u24_e32 v50, v58, v73
	v_lshl_add_u64 v[48:49], v[56:57], 0, v[68:69]
	v_lshlrev_b32_e32 v68, 2, v50
	v_mul_u32_u24_e32 v59, v58, v75
	v_lshl_add_u64 v[50:51], v[56:57], 0, v[68:69]
	v_lshlrev_b32_e32 v68, 2, v59
	v_mul_u32_u24_e32 v58, v58, v77
	v_lshl_add_u64 v[60:61], v[56:57], 0, v[68:69]
	v_lshlrev_b32_e32 v68, 2, v58
	v_mov_b32_e32 v81, v69
	v_lshl_add_u64 v[56:57], v[56:57], 0, v[68:69]
	v_lshl_add_u64 v[32:33], v[32:33], 0, v[80:81]
	v_lshl_add_u64 v[34:35], v[34:35], 0, v[80:81]
	v_lshl_add_u64 v[40:41], v[40:41], 0, v[80:81]
	v_lshl_add_u64 v[42:43], v[42:43], 0, v[80:81]
	v_lshl_add_u64 v[48:49], v[48:49], 0, v[80:81]
	v_lshl_add_u64 v[50:51], v[50:51], 0, v[80:81]
	v_lshl_add_u64 v[60:61], v[60:61], 0, v[80:81]
	v_lshl_add_u64 v[56:57], v[56:57], 0, v[80:81]
	global_load_dwordx4 v[36:39], v[32:33], off nt
	s_nop 0
	global_load_dwordx4 v[32:35], v[34:35], off nt
	s_nop 0
	global_load_dwordx4 v[44:47], v[40:41], off nt
	s_nop 0
	global_load_dwordx4 v[40:43], v[42:43], off nt
	s_nop 0
	global_load_dwordx4 v[52:55], v[48:49], off nt
	s_nop 0
	global_load_dwordx4 v[48:51], v[50:51], off nt
	s_nop 0
	global_load_dwordx4 v[60:63], v[60:61], off nt
	s_nop 0
	global_load_dwordx4 v[56:59], v[56:57], off nt
